# residual epilogues (Down/out0/out1): X-load pipeline depth 12 -> 24 tuples in flight
# baseline (speedup 1.0000x reference)
.LBB0_363:
	s_lshl_b32 s31, s11, 8
	s_min_i32 s20, s11, 0x100
	s_ashr_i32 s62, s20, 5
	s_add_i32 s63, s31, 0xffff0000
	s_cmpk_gt_i32 s11, 0xff
	s_cselect_b32 s11, s63, s31
	v_add_u32_e32 v146, s11, v1
	s_mul_i32 s62, s62, 0x9000
	s_cselect_b32 s23, s69, s65
	s_cselect_b32 s22, s70, s68
	s_cselect_b32 s21, s37, s49
	s_cselect_b32 s20, s33, s48
	v_lshl_or_b32 v147, s92, 8, v149
	v_lshlrev_b32_e32 v147, 2, v147
	v_lshl_add_u32 v146, v146, 12, v147
	v_add_u32_e32 v147, s62, v147
	v_add_co_u32_e32 v160, vcc, s75, v147
	v_mov_b32_e32 v161, s76
	s_nop 1
	v_addc_co_u32_e32 v161, vcc, 0, v161, vcc
	global_load_dwordx4 v[138:141], v[160:161], off
	global_load_dwordx4 v[142:145], v146, s[22:23]
	s_add_u32 s62, s22, 0x10000
	s_addc_u32 s63, s23, 0
	global_load_dwordx4 v[152:155], v146, s[62:63]
	s_add_u32 s62, s22, 0x20000
	s_addc_u32 s63, s23, 0
	global_load_dwordx4 v[156:159], v146, s[62:63]
	s_add_u32 s62, s22, 0x30000
	s_addc_u32 s63, s23, 0
	global_load_dwordx4 v[164:167], v146, s[62:63]
	s_add_u32 s62, s22, 0x80000
	s_addc_u32 s63, s23, 0
	global_load_dwordx4 v[168:171], v146, s[62:63]
	s_add_u32 s62, s22, 0x90000
	s_addc_u32 s63, s23, 0
	global_load_dwordx4 v[172:175], v146, s[62:63]
	s_add_u32 s62, s22, 0xa0000
	s_addc_u32 s63, s23, 0
	global_load_dwordx4 v[176:179], v146, s[62:63]
	s_add_u32 s62, s22, 0xb0000
	s_addc_u32 s63, s23, 0
	global_load_dwordx4 v[180:183], v146, s[62:63]
	global_load_dwordx4 v[184:187], v146, s[22:23] offset:64
	s_add_u32 s62, s22, 0x10000
	s_addc_u32 s63, s23, 0
	global_load_dwordx4 v[188:191], v146, s[62:63] offset:64
	s_add_u32 s62, s22, 0x20000
	s_addc_u32 s63, s23, 0
	global_load_dwordx4 v[192:195], v146, s[62:63] offset:64
	s_add_u32 s62, s22, 0x30000
	s_addc_u32 s63, s23, 0
	global_load_dwordx4 v[196:199], v146, s[62:63] offset:64
	s_add_u32 s62, s22, 0x80000
	s_addc_u32 s63, s23, 0
	global_load_dwordx4 v[200:203], v146, s[62:63] offset:64
	s_waitcnt vmcnt(13)
	v_pk_mul_f32 v[138:139], v[138:139], 0.5 op_sel_hi:[1,0]
	v_pk_mul_f32 v[140:141], v[140:141], 0.5 op_sel_hi:[1,0]
	s_waitcnt vmcnt(12)
	v_pk_fma_f32 v[142:143], v[126:127], v[138:139], v[142:143]
	v_pk_fma_f32 v[144:145], v[128:129], v[140:141], v[144:145]
	global_store_dwordx4 v146, v[142:145], s[20:21]
	s_add_u32 s62, s22, 0x90000
	s_addc_u32 s63, s23, 0
	global_load_dwordx4 v[126:129], v146, s[62:63] offset:64
	s_waitcnt vmcnt(13)
	v_pk_fma_f32 v[152:153], v[122:123], v[138:139], v[152:153]
	v_pk_fma_f32 v[154:155], v[124:125], v[140:141], v[154:155]
	s_add_u32 vcc_lo, s20, 0x10000
	s_addc_u32 vcc_hi, s21, 0
	global_store_dwordx4 v146, v[152:155], vcc
	s_add_u32 s62, s22, 0xa0000
	s_addc_u32 s63, s23, 0
	global_load_dwordx4 v[142:145], v146, s[62:63] offset:64
	s_add_u32 s62, s22, 0xb0000
	s_addc_u32 s63, s23, 0
	global_load_dwordx4 v[122:125], v146, s[62:63] offset:64
	s_waitcnt vmcnt(15)
	v_pk_fma_f32 v[156:157], v[118:119], v[138:139], v[156:157]
	v_pk_fma_f32 v[158:159], v[120:121], v[140:141], v[158:159]
	s_add_u32 vcc_lo, s20, 0x20000
	s_addc_u32 vcc_hi, s21, 0
	global_store_dwordx4 v146, v[156:159], vcc
	global_load_dwordx4 v[152:155], v146, s[22:23] offset:512
	s_add_u32 s62, s22, 0x10000
	s_addc_u32 s63, s23, 0
	global_load_dwordx4 v[118:121], v146, s[62:63] offset:512
	s_waitcnt vmcnt(17)
	v_pk_fma_f32 v[164:165], v[114:115], v[138:139], v[164:165]
	v_pk_fma_f32 v[166:167], v[116:117], v[140:141], v[166:167]
	s_add_u32 vcc_lo, s20, 0x30000
	s_addc_u32 vcc_hi, s21, 0
	global_store_dwordx4 v146, v[164:167], vcc
	global_load_dwordx4 v[156:159], v[160:161], off offset:64
	s_add_u32 s62, s22, 0x20000
	s_addc_u32 s63, s23, 0
	global_load_dwordx4 v[114:117], v146, s[62:63] offset:512
	s_add_u32 s62, s22, 0x30000
	s_addc_u32 s63, s23, 0
	global_load_dwordx4 v[164:167], v146, s[62:63] offset:512
	s_waitcnt vmcnt(20)
	v_pk_fma_f32 v[168:169], v[110:111], v[138:139], v[168:169]
	v_pk_fma_f32 v[170:171], v[112:113], v[140:141], v[170:171]
	s_add_u32 vcc_lo, s20, 0x80000
	s_addc_u32 vcc_hi, s21, 0
	global_store_dwordx4 v146, v[168:171], vcc
	s_add_u32 s62, s22, 0x80000
	s_addc_u32 s63, s23, 0
	global_load_dwordx4 v[110:113], v146, s[62:63] offset:512
	s_add_u32 s62, s22, 0x90000
	s_addc_u32 s63, s23, 0
	global_load_dwordx4 v[168:171], v146, s[62:63] offset:512
	s_waitcnt vmcnt(22)
	v_pk_fma_f32 v[172:173], v[106:107], v[138:139], v[172:173]
	v_pk_fma_f32 v[174:175], v[108:109], v[140:141], v[174:175]
	s_add_u32 vcc_lo, s20, 0x90000
	s_addc_u32 vcc_hi, s21, 0
	global_store_dwordx4 v146, v[172:175], vcc
	s_add_u32 s62, s22, 0xa0000
	s_addc_u32 s63, s23, 0
	global_load_dwordx4 v[106:109], v146, s[62:63] offset:512
	s_add_u32 s62, s22, 0xb0000
	s_addc_u32 s63, s23, 0
	global_load_dwordx4 v[172:175], v146, s[62:63] offset:512
	s_waitcnt vmcnt(24)
	v_pk_fma_f32 v[176:177], v[102:103], v[138:139], v[176:177]
	v_pk_fma_f32 v[178:179], v[104:105], v[140:141], v[178:179]
	s_add_u32 vcc_lo, s20, 0xa0000
	s_addc_u32 vcc_hi, s21, 0
	global_store_dwordx4 v146, v[176:179], vcc
	global_load_dwordx4 v[102:105], v146, s[22:23] offset:576
	s_add_u32 s62, s22, 0x10000
	s_addc_u32 s63, s23, 0
	global_load_dwordx4 v[176:179], v146, s[62:63] offset:576
	s_waitcnt vmcnt(26)
	v_pk_fma_f32 v[180:181], v[98:99], v[138:139], v[180:181]
	v_pk_fma_f32 v[182:183], v[100:101], v[140:141], v[182:183]
	s_add_u32 vcc_lo, s20, 0xb0000
	s_addc_u32 vcc_hi, s21, 0
	global_store_dwordx4 v146, v[180:183], vcc
	s_add_u32 s62, s22, 0x20000
	s_addc_u32 s63, s23, 0
	global_load_dwordx4 v[98:101], v146, s[62:63] offset:576
	s_add_u32 s62, s22, 0x30000
	s_addc_u32 s63, s23, 0
	global_load_dwordx4 v[180:183], v146, s[62:63] offset:576
	s_add_u32 s62, s22, 0x80000
	s_addc_u32 s63, s23, 0
	global_load_dwordx4 v[138:141], v146, s[62:63] offset:576
	s_waitcnt vmcnt(15)
	v_pk_mul_f32 v[156:157], v[156:157], 0.5 op_sel_hi:[1,0]
	v_pk_mul_f32 v[158:159], v[158:159], 0.5 op_sel_hi:[1,0]
	s_waitcnt vmcnt(29)
	v_pk_fma_f32 v[184:185], v[94:95], v[156:157], v[184:185]
	v_pk_fma_f32 v[186:187], v[96:97], v[158:159], v[186:187]
	global_store_dwordx4 v146, v[184:187], s[20:21] offset:64
	s_add_u32 s62, s22, 0x90000
	s_addc_u32 s63, s23, 0
	global_load_dwordx4 v[94:97], v146, s[62:63] offset:576
	s_waitcnt vmcnt(30)
	v_pk_fma_f32 v[188:189], v[90:91], v[156:157], v[188:189]
	v_pk_fma_f32 v[190:191], v[92:93], v[158:159], v[190:191]
	s_add_u32 vcc_lo, s20, 0x10000
	s_addc_u32 vcc_hi, s21, 0
	global_store_dwordx4 v146, v[188:191], vcc offset:64
	s_add_u32 s62, s22, 0xa0000
	s_addc_u32 s63, s23, 0
	global_load_dwordx4 v[184:187], v146, s[62:63] offset:576
	s_add_u32 s62, s22, 0xb0000
	s_addc_u32 s63, s23, 0
	global_load_dwordx4 v[90:93], v146, s[62:63] offset:576
	s_waitcnt vmcnt(32)
	v_pk_fma_f32 v[192:193], v[86:87], v[156:157], v[192:193]
	v_pk_fma_f32 v[194:195], v[88:89], v[158:159], v[194:195]
	s_add_u32 vcc_lo, s20, 0x20000
	s_addc_u32 vcc_hi, s21, 0
	global_store_dwordx4 v146, v[192:195], vcc offset:64
	s_waitcnt vmcnt(32)
	v_pk_fma_f32 v[196:197], v[82:83], v[156:157], v[196:197]
	v_pk_fma_f32 v[198:199], v[84:85], v[158:159], v[198:199]
	s_add_u32 vcc_lo, s20, 0x30000
	s_addc_u32 vcc_hi, s21, 0
	global_store_dwordx4 v146, v[196:199], vcc offset:64
	global_load_dwordx4 v[188:191], v[160:161], off offset:512
	s_waitcnt vmcnt(33)
	v_pk_fma_f32 v[200:201], v[78:79], v[156:157], v[200:201]
	v_pk_fma_f32 v[202:203], v[80:81], v[158:159], v[202:203]
	s_add_u32 vcc_lo, s20, 0x80000
	s_addc_u32 vcc_hi, s21, 0
	global_store_dwordx4 v146, v[200:203], vcc offset:64
	s_waitcnt vmcnt(32)
	v_pk_fma_f32 v[126:127], v[74:75], v[156:157], v[126:127]
	v_pk_fma_f32 v[128:129], v[76:77], v[158:159], v[128:129]
	s_add_u32 vcc_lo, s20, 0x90000
	s_addc_u32 vcc_hi, s21, 0
	global_store_dwordx4 v146, v[126:129], vcc offset:64
	s_waitcnt vmcnt(31)
	v_pk_fma_f32 v[142:143], v[70:71], v[156:157], v[142:143]
	v_pk_fma_f32 v[144:145], v[72:73], v[158:159], v[144:145]
	s_add_u32 vcc_lo, s20, 0xa0000
	s_addc_u32 vcc_hi, s21, 0
	global_store_dwordx4 v146, v[142:145], vcc offset:64
	s_waitcnt vmcnt(31)
	v_pk_fma_f32 v[122:123], v[66:67], v[156:157], v[122:123]
	v_pk_fma_f32 v[124:125], v[68:69], v[158:159], v[124:125]
	s_add_u32 vcc_lo, s20, 0xb0000
	s_addc_u32 vcc_hi, s21, 0
	global_store_dwordx4 v146, v[122:125], vcc offset:64
	s_waitcnt vmcnt(4)
	v_pk_mul_f32 v[188:189], v[188:189], 0.5 op_sel_hi:[1,0]
	v_pk_mul_f32 v[190:191], v[190:191], 0.5 op_sel_hi:[1,0]
	s_waitcnt vmcnt(30)
	v_pk_fma_f32 v[152:153], v[62:63], v[188:189], v[152:153]
	v_pk_fma_f32 v[154:155], v[64:65], v[190:191], v[154:155]
	global_store_dwordx4 v146, v[152:155], s[20:21] offset:512
	s_waitcnt vmcnt(30)
	v_pk_fma_f32 v[118:119], v[58:59], v[188:189], v[118:119]
	v_pk_fma_f32 v[120:121], v[60:61], v[190:191], v[120:121]
	s_add_u32 vcc_lo, s20, 0x10000
	s_addc_u32 vcc_hi, s21, 0
	global_store_dwordx4 v146, v[118:121], vcc offset:512
	s_waitcnt vmcnt(28)
	v_pk_fma_f32 v[114:115], v[54:55], v[188:189], v[114:115]
	v_pk_fma_f32 v[116:117], v[56:57], v[190:191], v[116:117]
	s_add_u32 vcc_lo, s20, 0x20000
	s_addc_u32 vcc_hi, s21, 0
	global_store_dwordx4 v146, v[114:117], vcc offset:512
	s_waitcnt vmcnt(28)
	v_pk_fma_f32 v[164:165], v[50:51], v[188:189], v[164:165]
	v_pk_fma_f32 v[166:167], v[52:53], v[190:191], v[166:167]
	s_add_u32 vcc_lo, s20, 0x30000
	s_addc_u32 vcc_hi, s21, 0
	global_store_dwordx4 v146, v[164:167], vcc offset:512
	global_load_dwordx4 v[86:89], v[160:161], off offset:576
	s_waitcnt vmcnt(28)
	v_pk_fma_f32 v[110:111], v[46:47], v[188:189], v[110:111]
	v_pk_fma_f32 v[112:113], v[48:49], v[190:191], v[112:113]
	s_add_u32 vcc_lo, s20, 0x80000
	s_addc_u32 vcc_hi, s21, 0
	global_store_dwordx4 v146, v[110:113], vcc offset:512
	s_waitcnt vmcnt(28)
	v_pk_fma_f32 v[168:169], v[42:43], v[188:189], v[168:169]
	v_pk_fma_f32 v[170:171], v[44:45], v[190:191], v[170:171]
	s_add_u32 vcc_lo, s20, 0x90000
	s_addc_u32 vcc_hi, s21, 0
	global_store_dwordx4 v146, v[168:171], vcc offset:512
	s_waitcnt vmcnt(27)
	v_pk_fma_f32 v[106:107], v[38:39], v[188:189], v[106:107]
	v_pk_fma_f32 v[108:109], v[40:41], v[190:191], v[108:109]
	s_add_u32 vcc_lo, s20, 0xa0000
	s_addc_u32 vcc_hi, s21, 0
	global_store_dwordx4 v146, v[106:109], vcc offset:512
	s_waitcnt vmcnt(27)
	v_pk_fma_f32 v[172:173], v[34:35], v[188:189], v[172:173]
	v_pk_fma_f32 v[174:175], v[36:37], v[190:191], v[174:175]
	s_add_u32 vcc_lo, s20, 0xb0000
	s_addc_u32 vcc_hi, s21, 0
	global_store_dwordx4 v146, v[172:175], vcc offset:512
	s_waitcnt vmcnt(4)
	v_pk_mul_f32 v[86:87], v[86:87], 0.5 op_sel_hi:[1,0]
	v_pk_mul_f32 v[88:89], v[88:89], 0.5 op_sel_hi:[1,0]
	s_waitcnt vmcnt(26)
	v_pk_fma_f32 v[102:103], v[30:31], v[86:87], v[102:103]
	v_pk_fma_f32 v[104:105], v[32:33], v[88:89], v[104:105]
	global_store_dwordx4 v146, v[102:105], s[20:21] offset:576
	s_waitcnt vmcnt(26)
	v_pk_fma_f32 v[176:177], v[26:27], v[86:87], v[176:177]
	v_pk_fma_f32 v[178:179], v[28:29], v[88:89], v[178:179]
	s_add_u32 vcc_lo, s20, 0x10000
	s_addc_u32 vcc_hi, s21, 0
	global_store_dwordx4 v146, v[176:179], vcc offset:576
	s_waitcnt vmcnt(25)
	v_pk_fma_f32 v[98:99], v[22:23], v[86:87], v[98:99]
	v_pk_fma_f32 v[100:101], v[24:25], v[88:89], v[100:101]
	s_add_u32 vcc_lo, s20, 0x20000
	s_addc_u32 vcc_hi, s21, 0
	global_store_dwordx4 v146, v[98:101], vcc offset:576
	s_waitcnt vmcnt(25)
	v_pk_fma_f32 v[180:181], v[18:19], v[86:87], v[180:181]
	v_pk_fma_f32 v[182:183], v[20:21], v[88:89], v[182:183]
	s_add_u32 vcc_lo, s20, 0x30000
	s_addc_u32 vcc_hi, s21, 0
	global_store_dwordx4 v146, v[180:183], vcc offset:576
	s_waitcnt vmcnt(25)
	v_pk_fma_f32 v[138:139], v[14:15], v[86:87], v[138:139]
	v_pk_fma_f32 v[140:141], v[16:17], v[88:89], v[140:141]
	s_add_u32 vcc_lo, s20, 0x80000
	s_addc_u32 vcc_hi, s21, 0
	global_store_dwordx4 v146, v[138:141], vcc offset:576
	s_waitcnt vmcnt(24)
	v_pk_fma_f32 v[94:95], v[10:11], v[86:87], v[94:95]
	v_pk_fma_f32 v[96:97], v[12:13], v[88:89], v[96:97]
	s_add_u32 vcc_lo, s20, 0x90000
	s_addc_u32 vcc_hi, s21, 0
	global_store_dwordx4 v146, v[94:97], vcc offset:576
	s_waitcnt vmcnt(23)
	v_pk_fma_f32 v[184:185], v[6:7], v[86:87], v[184:185]
	v_pk_fma_f32 v[186:187], v[8:9], v[88:89], v[186:187]
	s_add_u32 vcc_lo, s20, 0xa0000
	s_addc_u32 vcc_hi, s21, 0
	global_store_dwordx4 v146, v[184:187], vcc offset:576
	s_waitcnt vmcnt(23)
	v_pk_fma_f32 v[90:91], v[2:3], v[86:87], v[90:91]
	v_pk_fma_f32 v[92:93], v[4:5], v[88:89], v[92:93]
	s_add_u32 vcc_lo, s20, 0xb0000
	s_addc_u32 vcc_hi, s21, 0
	global_store_dwordx4 v146, v[90:93], vcc offset:576
	s_mov_b32 s11, 0
	s_mov_b64 s[62:63], 0xb0000
	s_mov_b64 s[20:21], -1
	s_and_b64 vcc, exec, s[0:1]
	s_cbranch_vccnz .LBB0_351
	s_andn2_b64 vcc, exec, s[14:15]
	s_cbranch_vccnz .LBB0_350
	s_barrier
	s_branch .LBB0_350

.LBB0_1015:
	s_lshl_b32 s20, s11, 8
	s_min_i32 s18, s11, 0x100
	s_ashr_i32 s21, s18, 5
	s_add_i32 s31, s20, 0xffff0000
	s_cmpk_gt_i32 s11, 0xff
	s_cselect_b32 s11, s31, s20
	v_add_u32_e32 v154, s11, v1
	v_lshl_or_b32 v155, s10, 8, v147
	s_mul_i32 s21, s21, 0x9000
	s_cselect_b32 s19, s37, s49
	s_cselect_b32 s18, s33, s48
	v_lshlrev_b32_e32 v155, 2, v155
	v_lshl_add_u32 v154, v154, 12, v155
	v_add_u32_e32 v155, s21, v155
	v_readlane_b32 s10, v255, 11
	v_readlane_b32 s20, v255, 13
	s_nop 1
	v_add_co_u32_e32 v156, vcc, s10, v155
	v_mov_b32_e32 v157, s20
	s_nop 1
	v_addc_co_u32_e32 v157, vcc, 0, v157, vcc
	global_load_dwordx4 v[130:133], v[156:157], off
	global_load_dwordx4 v[142:145], v154, s[18:19]
	s_add_u32 s10, s18, 0x10000
	s_addc_u32 s11, s19, 0
	global_load_dwordx4 v[150:153], v154, s[10:11]
	s_add_u32 s10, s18, 0x20000
	s_addc_u32 s11, s19, 0
	global_load_dwordx4 v[158:161], v154, s[10:11]
	s_add_u32 s10, s18, 0x30000
	s_addc_u32 s11, s19, 0
	global_load_dwordx4 v[162:165], v154, s[10:11]
	s_add_u32 s10, s18, 0x80000
	s_addc_u32 s11, s19, 0
	global_load_dwordx4 v[166:169], v154, s[10:11]
	s_add_u32 s10, s18, 0x90000
	s_addc_u32 s11, s19, 0
	global_load_dwordx4 v[170:173], v154, s[10:11]
	s_add_u32 s10, s18, 0xa0000
	s_addc_u32 s11, s19, 0
	global_load_dwordx4 v[174:177], v154, s[10:11]
	s_add_u32 s10, s18, 0xb0000
	s_addc_u32 s11, s19, 0
	global_load_dwordx4 v[178:181], v154, s[10:11]
	global_load_dwordx4 v[182:185], v154, s[18:19] offset:64
	s_add_u32 s10, s18, 0x10000
	s_addc_u32 s11, s19, 0
	global_load_dwordx4 v[186:189], v154, s[10:11] offset:64
	s_add_u32 s10, s18, 0x20000
	s_addc_u32 s11, s19, 0
	global_load_dwordx4 v[190:193], v154, s[10:11] offset:64
	s_add_u32 s10, s18, 0x30000
	s_addc_u32 s11, s19, 0
	global_load_dwordx4 v[194:197], v154, s[10:11] offset:64
	s_add_u32 s10, s18, 0x80000
	s_addc_u32 s11, s19, 0
	global_load_dwordx4 v[198:201], v154, s[10:11] offset:64
	s_waitcnt vmcnt(13)
	s_waitcnt vmcnt(12)
	v_pk_fma_f32 v[142:143], v[126:127], v[130:131], v[142:143]
	v_pk_fma_f32 v[144:145], v[128:129], v[132:133], v[144:145]
	global_store_dwordx4 v154, v[142:145], s[18:19]
	s_add_u32 s10, s18, 0x90000
	s_addc_u32 s11, s19, 0
	global_load_dwordx4 v[126:129], v154, s[10:11] offset:64
	s_waitcnt vmcnt(13)
	v_pk_fma_f32 v[150:151], v[122:123], v[130:131], v[150:151]
	v_pk_fma_f32 v[152:153], v[124:125], v[132:133], v[152:153]
	s_add_u32 vcc_lo, s18, 0x10000
	s_addc_u32 vcc_hi, s19, 0
	global_store_dwordx4 v154, v[150:153], vcc
	s_add_u32 s10, s18, 0xa0000
	s_addc_u32 s11, s19, 0
	global_load_dwordx4 v[142:145], v154, s[10:11] offset:64
	s_add_u32 s10, s18, 0xb0000
	s_addc_u32 s11, s19, 0
	global_load_dwordx4 v[122:125], v154, s[10:11] offset:64
	s_waitcnt vmcnt(15)
	v_pk_fma_f32 v[158:159], v[118:119], v[130:131], v[158:159]
	v_pk_fma_f32 v[160:161], v[120:121], v[132:133], v[160:161]
	s_add_u32 vcc_lo, s18, 0x20000
	s_addc_u32 vcc_hi, s19, 0
	global_store_dwordx4 v154, v[158:161], vcc
	global_load_dwordx4 v[150:153], v154, s[18:19] offset:512
	s_add_u32 s10, s18, 0x10000
	s_addc_u32 s11, s19, 0
	global_load_dwordx4 v[118:121], v154, s[10:11] offset:512
	s_waitcnt vmcnt(17)
	v_pk_fma_f32 v[162:163], v[114:115], v[130:131], v[162:163]
	v_pk_fma_f32 v[164:165], v[116:117], v[132:133], v[164:165]
	s_add_u32 vcc_lo, s18, 0x30000
	s_addc_u32 vcc_hi, s19, 0
	global_store_dwordx4 v154, v[162:165], vcc
	global_load_dwordx4 v[158:161], v[156:157], off offset:64
	s_add_u32 s10, s18, 0x20000
	s_addc_u32 s11, s19, 0
	global_load_dwordx4 v[114:117], v154, s[10:11] offset:512
	s_add_u32 s10, s18, 0x30000
	s_addc_u32 s11, s19, 0
	global_load_dwordx4 v[162:165], v154, s[10:11] offset:512
	s_waitcnt vmcnt(20)
	v_pk_fma_f32 v[166:167], v[110:111], v[130:131], v[166:167]
	v_pk_fma_f32 v[168:169], v[112:113], v[132:133], v[168:169]
	s_add_u32 vcc_lo, s18, 0x80000
	s_addc_u32 vcc_hi, s19, 0
	global_store_dwordx4 v154, v[166:169], vcc
	s_add_u32 s10, s18, 0x80000
	s_addc_u32 s11, s19, 0
	global_load_dwordx4 v[110:113], v154, s[10:11] offset:512
	s_add_u32 s10, s18, 0x90000
	s_addc_u32 s11, s19, 0
	global_load_dwordx4 v[166:169], v154, s[10:11] offset:512
	s_waitcnt vmcnt(22)
	v_pk_fma_f32 v[170:171], v[106:107], v[130:131], v[170:171]
	v_pk_fma_f32 v[172:173], v[108:109], v[132:133], v[172:173]
	s_add_u32 vcc_lo, s18, 0x90000
	s_addc_u32 vcc_hi, s19, 0
	global_store_dwordx4 v154, v[170:173], vcc
	s_add_u32 s10, s18, 0xa0000
	s_addc_u32 s11, s19, 0
	global_load_dwordx4 v[106:109], v154, s[10:11] offset:512
	s_add_u32 s10, s18, 0xb0000
	s_addc_u32 s11, s19, 0
	global_load_dwordx4 v[170:173], v154, s[10:11] offset:512
	s_waitcnt vmcnt(24)
	v_pk_fma_f32 v[174:175], v[102:103], v[130:131], v[174:175]
	v_pk_fma_f32 v[176:177], v[104:105], v[132:133], v[176:177]
	s_add_u32 vcc_lo, s18, 0xa0000
	s_addc_u32 vcc_hi, s19, 0
	global_store_dwordx4 v154, v[174:177], vcc
	global_load_dwordx4 v[102:105], v154, s[18:19] offset:576
	s_add_u32 s10, s18, 0x10000
	s_addc_u32 s11, s19, 0
	global_load_dwordx4 v[174:177], v154, s[10:11] offset:576
	s_waitcnt vmcnt(26)
	v_pk_fma_f32 v[178:179], v[98:99], v[130:131], v[178:179]
	v_pk_fma_f32 v[180:181], v[100:101], v[132:133], v[180:181]
	s_add_u32 vcc_lo, s18, 0xb0000
	s_addc_u32 vcc_hi, s19, 0
	global_store_dwordx4 v154, v[178:181], vcc
	s_add_u32 s10, s18, 0x20000
	s_addc_u32 s11, s19, 0
	global_load_dwordx4 v[98:101], v154, s[10:11] offset:576
	s_add_u32 s10, s18, 0x30000
	s_addc_u32 s11, s19, 0
	global_load_dwordx4 v[178:181], v154, s[10:11] offset:576
	s_add_u32 s10, s18, 0x80000
	s_addc_u32 s11, s19, 0
	global_load_dwordx4 v[130:133], v154, s[10:11] offset:576
	s_waitcnt vmcnt(15)
	s_waitcnt vmcnt(29)
	v_pk_fma_f32 v[182:183], v[94:95], v[158:159], v[182:183]
	v_pk_fma_f32 v[184:185], v[96:97], v[160:161], v[184:185]
	global_store_dwordx4 v154, v[182:185], s[18:19] offset:64
	s_add_u32 s10, s18, 0x90000
	s_addc_u32 s11, s19, 0
	global_load_dwordx4 v[94:97], v154, s[10:11] offset:576
	s_waitcnt vmcnt(30)
	v_pk_fma_f32 v[186:187], v[90:91], v[158:159], v[186:187]
	v_pk_fma_f32 v[188:189], v[92:93], v[160:161], v[188:189]
	s_add_u32 vcc_lo, s18, 0x10000
	s_addc_u32 vcc_hi, s19, 0
	global_store_dwordx4 v154, v[186:189], vcc offset:64
	s_add_u32 s10, s18, 0xa0000
	s_addc_u32 s11, s19, 0
	global_load_dwordx4 v[182:185], v154, s[10:11] offset:576
	s_add_u32 s10, s18, 0xb0000
	s_addc_u32 s11, s19, 0
	global_load_dwordx4 v[90:93], v154, s[10:11] offset:576
	s_waitcnt vmcnt(32)
	v_pk_fma_f32 v[190:191], v[86:87], v[158:159], v[190:191]
	v_pk_fma_f32 v[192:193], v[88:89], v[160:161], v[192:193]
	s_add_u32 vcc_lo, s18, 0x20000
	s_addc_u32 vcc_hi, s19, 0
	global_store_dwordx4 v154, v[190:193], vcc offset:64
	s_waitcnt vmcnt(32)
	v_pk_fma_f32 v[194:195], v[82:83], v[158:159], v[194:195]
	v_pk_fma_f32 v[196:197], v[84:85], v[160:161], v[196:197]
	s_add_u32 vcc_lo, s18, 0x30000
	s_addc_u32 vcc_hi, s19, 0
	global_store_dwordx4 v154, v[194:197], vcc offset:64
	global_load_dwordx4 v[186:189], v[156:157], off offset:512
	s_waitcnt vmcnt(33)
	v_pk_fma_f32 v[198:199], v[78:79], v[158:159], v[198:199]
	v_pk_fma_f32 v[200:201], v[80:81], v[160:161], v[200:201]
	s_add_u32 vcc_lo, s18, 0x80000
	s_addc_u32 vcc_hi, s19, 0
	global_store_dwordx4 v154, v[198:201], vcc offset:64
	s_waitcnt vmcnt(32)
	v_pk_fma_f32 v[126:127], v[74:75], v[158:159], v[126:127]
	v_pk_fma_f32 v[128:129], v[76:77], v[160:161], v[128:129]
	s_add_u32 vcc_lo, s18, 0x90000
	s_addc_u32 vcc_hi, s19, 0
	global_store_dwordx4 v154, v[126:129], vcc offset:64
	s_waitcnt vmcnt(31)
	v_pk_fma_f32 v[142:143], v[70:71], v[158:159], v[142:143]
	v_pk_fma_f32 v[144:145], v[72:73], v[160:161], v[144:145]
	s_add_u32 vcc_lo, s18, 0xa0000
	s_addc_u32 vcc_hi, s19, 0
	global_store_dwordx4 v154, v[142:145], vcc offset:64
	s_waitcnt vmcnt(31)
	v_pk_fma_f32 v[122:123], v[66:67], v[158:159], v[122:123]
	v_pk_fma_f32 v[124:125], v[68:69], v[160:161], v[124:125]
	s_add_u32 vcc_lo, s18, 0xb0000
	s_addc_u32 vcc_hi, s19, 0
	global_store_dwordx4 v154, v[122:125], vcc offset:64
	s_waitcnt vmcnt(4)
	s_waitcnt vmcnt(30)
	v_pk_fma_f32 v[150:151], v[62:63], v[186:187], v[150:151]
	v_pk_fma_f32 v[152:153], v[64:65], v[188:189], v[152:153]
	global_store_dwordx4 v154, v[150:153], s[18:19] offset:512
	s_waitcnt vmcnt(30)
	v_pk_fma_f32 v[118:119], v[58:59], v[186:187], v[118:119]
	v_pk_fma_f32 v[120:121], v[60:61], v[188:189], v[120:121]
	s_add_u32 vcc_lo, s18, 0x10000
	s_addc_u32 vcc_hi, s19, 0
	global_store_dwordx4 v154, v[118:121], vcc offset:512
	s_waitcnt vmcnt(28)
	v_pk_fma_f32 v[114:115], v[54:55], v[186:187], v[114:115]
	v_pk_fma_f32 v[116:117], v[56:57], v[188:189], v[116:117]
	s_add_u32 vcc_lo, s18, 0x20000
	s_addc_u32 vcc_hi, s19, 0
	global_store_dwordx4 v154, v[114:117], vcc offset:512
	s_waitcnt vmcnt(28)
	v_pk_fma_f32 v[162:163], v[50:51], v[186:187], v[162:163]
	v_pk_fma_f32 v[164:165], v[52:53], v[188:189], v[164:165]
	s_add_u32 vcc_lo, s18, 0x30000
	s_addc_u32 vcc_hi, s19, 0
	global_store_dwordx4 v154, v[162:165], vcc offset:512
	global_load_dwordx4 v[86:89], v[156:157], off offset:576
	s_waitcnt vmcnt(28)
	v_pk_fma_f32 v[110:111], v[46:47], v[186:187], v[110:111]
	v_pk_fma_f32 v[112:113], v[48:49], v[188:189], v[112:113]
	s_add_u32 vcc_lo, s18, 0x80000
	s_addc_u32 vcc_hi, s19, 0
	global_store_dwordx4 v154, v[110:113], vcc offset:512
	s_waitcnt vmcnt(28)
	v_pk_fma_f32 v[166:167], v[42:43], v[186:187], v[166:167]
	v_pk_fma_f32 v[168:169], v[44:45], v[188:189], v[168:169]
	s_add_u32 vcc_lo, s18, 0x90000
	s_addc_u32 vcc_hi, s19, 0
	global_store_dwordx4 v154, v[166:169], vcc offset:512
	s_waitcnt vmcnt(27)
	v_pk_fma_f32 v[106:107], v[38:39], v[186:187], v[106:107]
	v_pk_fma_f32 v[108:109], v[40:41], v[188:189], v[108:109]
	s_add_u32 vcc_lo, s18, 0xa0000
	s_addc_u32 vcc_hi, s19, 0
	global_store_dwordx4 v154, v[106:109], vcc offset:512
	s_waitcnt vmcnt(27)
	v_pk_fma_f32 v[170:171], v[34:35], v[186:187], v[170:171]
	v_pk_fma_f32 v[172:173], v[36:37], v[188:189], v[172:173]
	s_add_u32 vcc_lo, s18, 0xb0000
	s_addc_u32 vcc_hi, s19, 0
	global_store_dwordx4 v154, v[170:173], vcc offset:512
	s_waitcnt vmcnt(4)
	s_waitcnt vmcnt(26)
	v_pk_fma_f32 v[102:103], v[30:31], v[86:87], v[102:103]
	v_pk_fma_f32 v[104:105], v[32:33], v[88:89], v[104:105]
	global_store_dwordx4 v154, v[102:105], s[18:19] offset:576
	s_waitcnt vmcnt(26)
	v_pk_fma_f32 v[174:175], v[26:27], v[86:87], v[174:175]
	v_pk_fma_f32 v[176:177], v[28:29], v[88:89], v[176:177]
	s_add_u32 vcc_lo, s18, 0x10000
	s_addc_u32 vcc_hi, s19, 0
	global_store_dwordx4 v154, v[174:177], vcc offset:576
	s_waitcnt vmcnt(25)
	v_pk_fma_f32 v[98:99], v[22:23], v[86:87], v[98:99]
	v_pk_fma_f32 v[100:101], v[24:25], v[88:89], v[100:101]
	s_add_u32 vcc_lo, s18, 0x20000
	s_addc_u32 vcc_hi, s19, 0
	global_store_dwordx4 v154, v[98:101], vcc offset:576
	s_waitcnt vmcnt(25)
	v_pk_fma_f32 v[178:179], v[18:19], v[86:87], v[178:179]
	v_pk_fma_f32 v[180:181], v[20:21], v[88:89], v[180:181]
	s_add_u32 vcc_lo, s18, 0x30000
	s_addc_u32 vcc_hi, s19, 0
	global_store_dwordx4 v154, v[178:181], vcc offset:576
	s_waitcnt vmcnt(25)
	v_pk_fma_f32 v[130:131], v[14:15], v[86:87], v[130:131]
	v_pk_fma_f32 v[132:133], v[16:17], v[88:89], v[132:133]
	s_add_u32 vcc_lo, s18, 0x80000
	s_addc_u32 vcc_hi, s19, 0
	global_store_dwordx4 v154, v[130:133], vcc offset:576
	s_waitcnt vmcnt(24)
	v_pk_fma_f32 v[94:95], v[10:11], v[86:87], v[94:95]
	v_pk_fma_f32 v[96:97], v[12:13], v[88:89], v[96:97]
	s_add_u32 vcc_lo, s18, 0x90000
	s_addc_u32 vcc_hi, s19, 0
	global_store_dwordx4 v154, v[94:97], vcc offset:576
	s_waitcnt vmcnt(23)
	v_pk_fma_f32 v[182:183], v[6:7], v[86:87], v[182:183]
	v_pk_fma_f32 v[184:185], v[8:9], v[88:89], v[184:185]
	s_add_u32 vcc_lo, s18, 0xa0000
	s_addc_u32 vcc_hi, s19, 0
	global_store_dwordx4 v154, v[182:185], vcc offset:576
	s_waitcnt vmcnt(23)
	v_pk_fma_f32 v[90:91], v[2:3], v[86:87], v[90:91]
	v_pk_fma_f32 v[92:93], v[4:5], v[88:89], v[92:93]
	s_add_u32 vcc_lo, s18, 0xb0000
	s_addc_u32 vcc_hi, s19, 0
	global_store_dwordx4 v154, v[90:93], vcc offset:576
	s_mov_b64 s[10:11], 0xb0000
	s_mov_b64 s[18:19], -1
	s_and_b64 vcc, exec, s[0:1]
	s_cbranch_vccnz .LBB0_1003
	s_andn2_b64 vcc, exec, s[8:9]
	s_cbranch_vccnz .LBB0_1002
	s_barrier
	s_branch .LBB0_1002
